# scan: + static priority for the sample team, prep stage issues both passes LDS reads up front
# speedup vs baseline: 1.0195x; 1.0069x over previous
.Lsc_noctr:
	s_cmp_eq_u32 s38, 0
	s_cbranch_scc0 .Lsc_noprio
	s_setprio 1

.Lsc_isd_4:
	s_waitcnt vmcnt(0) lgkmcnt(0)
	s_barrier
	s_mov_b32 s33, 0
	s_lshr_b32 s54, s33, s3
	s_and_b32 s53, s33, s52
	s_lshl_b32 s54, s54, 11
	s_mul_i32 s55, s53, s1
	s_add_u32 s51, s0, s54
	s_add_u32 s51, s51, s55
	s_and_b32 s55, s33, 1
	s_mul_i32 s56, s55, 10496
	s_add_u32 s56, s56, s41
	s_mul_i32 s57, s55, 24576
	s_add_u32 s57, s57, s41
	s_add_u32 s57, s57, 20992
	s_sub_u32 s58, 0, s50
	s_and_b32 s58, s58, 15
	v_xor_b32_e32 v22, s58, v141
	v_add_u32_e32 v94, 2, v141
	v_lshl_add_u32 v23, v22, 7, v5
	v_lshlrev_b32_e32 v24, 2, v22
	v_xor_b32_e32 v94, s58, v94
	v_add_u32_e32 v23, s56, v23
	v_add_u32_e32 v24, s56, v24
	v_lshl_add_u32 v95, v94, 7, v5
	v_lshlrev_b32_e32 v96, 2, v94
	ds_read2st64_b32 v[26:27], v23 offset0:0 offset1:8
	ds_read2st64_b32 v[30:31], v23 offset0:16 offset1:24
	v_add_u32_e32 v95, s56, v95
	v_add_u32_e32 v96, s56, v96
	ds_read_b32 v29, v23 offset:8192
	ds_read_b32 v28, v24 offset:10240
	ds_read2st64_b32 v[98:99], v95 offset0:0 offset1:8
	ds_read2st64_b32 v[100:101], v95 offset0:16 offset1:24
	ds_read_b32 v97, v95 offset:8192
	ds_read_b32 v96, v96 offset:10240
	v_add_u32_e32 v25, s57, v140
	s_waitcnt lgkmcnt(4)
	v_cvt_f32_f16_e32 v32, v27
	v_cvt_f32_f16_sdwa v33, v27 dst_sel:DWORD dst_unused:UNUSED_PAD src0_sel:WORD_1
	v_cvt_f32_f16_e32 v34, v31
	v_cvt_f32_f16_sdwa v35, v31 dst_sel:DWORD dst_unused:UNUSED_PAD src0_sel:WORD_1
	v_pk_mul_f32 v[36:37], v[136:137], v[28:29] op_sel_hi:[1,0]
	v_cvt_f32_f16_e32 v42, v26
	v_cvt_f32_f16_sdwa v43, v26 dst_sel:DWORD dst_unused:UNUSED_PAD src0_sel:WORD_1
	v_pk_mul_f32 v[36:37], v[36:37], v[32:33]
	v_pk_add_f32 v[40:41], v[34:35], -1.0 op_sel_hi:[1,0]
	v_cvt_f32_f16_e32 v44, v30
	v_pk_mul_f32 v[38:39], v[36:37], v[34:35]
	v_pk_fma_f32 v[40:41], v[40:41], v[138:139], 1.0 op_sel_hi:[1,1,0]
	v_cvt_f32_f16_sdwa v45, v30 dst_sel:DWORD dst_unused:UNUSED_PAD src0_sel:WORD_1
	ds_write2st64_b64 v25, v[36:37], v[38:39] offset0:0 offset1:8
	v_pk_mul_f32 v[40:41], v[40:41], v[32:33]
	v_cvt_f32_f16_e32 v26, v29
	v_cvt_f32_f16_sdwa v27, v29 dst_sel:DWORD dst_unused:UNUSED_PAD src0_sel:WORD_1
	ds_write2st64_b64 v25, v[40:41], v[42:43] offset0:16 offset1:24
	s_nop 0
	ds_write2st64_b64 v25, v[44:45], v[26:27] offset0:32 offset1:40
	s_waitcnt lgkmcnt(3)
	v_mov_b32_e32 v26, v98
	v_mov_b32_e32 v27, v99
	v_mov_b32_e32 v30, v100
	v_mov_b32_e32 v31, v101
	v_mov_b32_e32 v29, v97
	v_mov_b32_e32 v28, v96
	v_cvt_f32_f16_e32 v32, v27
	v_cvt_f32_f16_sdwa v33, v27 dst_sel:DWORD dst_unused:UNUSED_PAD src0_sel:WORD_1
	v_cvt_f32_f16_e32 v34, v31
	v_cvt_f32_f16_sdwa v35, v31 dst_sel:DWORD dst_unused:UNUSED_PAD src0_sel:WORD_1
	v_pk_mul_f32 v[36:37], v[136:137], v[28:29] op_sel_hi:[1,0]
	v_cvt_f32_f16_e32 v42, v26
	v_cvt_f32_f16_sdwa v43, v26 dst_sel:DWORD dst_unused:UNUSED_PAD src0_sel:WORD_1
	v_pk_mul_f32 v[36:37], v[36:37], v[32:33]
	v_pk_add_f32 v[40:41], v[34:35], -1.0 op_sel_hi:[1,0]
	v_cvt_f32_f16_e32 v44, v30
	v_pk_mul_f32 v[38:39], v[36:37], v[34:35]
	v_pk_fma_f32 v[40:41], v[40:41], v[138:139], 1.0 op_sel_hi:[1,1,0]
	v_cvt_f32_f16_sdwa v45, v30 dst_sel:DWORD dst_unused:UNUSED_PAD src0_sel:WORD_1
	ds_write2st64_b64 v25, v[36:37], v[38:39] offset0:1 offset1:9
	v_pk_mul_f32 v[40:41], v[40:41], v[32:33]
	v_cvt_f32_f16_e32 v26, v29
	v_cvt_f32_f16_sdwa v27, v29 dst_sel:DWORD dst_unused:UNUSED_PAD src0_sel:WORD_1
	ds_write2st64_b64 v25, v[40:41], v[42:43] offset0:17 offset1:25
	s_nop 0
	ds_write2st64_b64 v25, v[44:45], v[26:27] offset0:33 offset1:41
	s_waitcnt lgkmcnt(0)
	s_barrier
	s_mov_b32 s33, 0

.Lsc_isd_6:
.Lsc_prep:
	s_add_u32 s47, s33, 1
	s_cmp_lt_u32 s47, s40
	s_cbranch_scc0 .Lsc_noprep
	s_lshr_b32 s54, s47, s3
	s_and_b32 s53, s47, s52
	s_lshl_b32 s54, s54, 11
	s_mul_i32 s55, s53, s1
	s_add_u32 s51, s0, s54
	s_add_u32 s51, s51, s55
	s_and_b32 s55, s47, 1
	s_mul_i32 s56, s55, 10496
	s_add_u32 s56, s56, s41
	s_mul_i32 s57, s55, 24576
	s_add_u32 s57, s57, s41
	s_add_u32 s57, s57, 20992
	s_sub_u32 s58, 0, s50
	s_and_b32 s58, s58, 15
	v_xor_b32_e32 v22, s58, v141
	v_add_u32_e32 v94, 2, v141
	v_lshl_add_u32 v23, v22, 7, v5
	v_lshlrev_b32_e32 v24, 2, v22
	v_xor_b32_e32 v94, s58, v94
	v_add_u32_e32 v23, s56, v23
	v_add_u32_e32 v24, s56, v24
	v_lshl_add_u32 v95, v94, 7, v5
	v_lshlrev_b32_e32 v96, 2, v94
	ds_read2st64_b32 v[26:27], v23 offset0:0 offset1:8
	ds_read2st64_b32 v[30:31], v23 offset0:16 offset1:24
	v_add_u32_e32 v95, s56, v95
	v_add_u32_e32 v96, s56, v96
	ds_read_b32 v29, v23 offset:8192
	ds_read_b32 v28, v24 offset:10240
	ds_read2st64_b32 v[98:99], v95 offset0:0 offset1:8
	ds_read2st64_b32 v[100:101], v95 offset0:16 offset1:24
	ds_read_b32 v97, v95 offset:8192
	ds_read_b32 v96, v96 offset:10240
	v_add_u32_e32 v25, s57, v140
	s_waitcnt lgkmcnt(4)
	v_cvt_f32_f16_e32 v32, v27
	v_cvt_f32_f16_sdwa v33, v27 dst_sel:DWORD dst_unused:UNUSED_PAD src0_sel:WORD_1
	v_cvt_f32_f16_e32 v34, v31
	v_cvt_f32_f16_sdwa v35, v31 dst_sel:DWORD dst_unused:UNUSED_PAD src0_sel:WORD_1
	v_pk_mul_f32 v[36:37], v[136:137], v[28:29] op_sel_hi:[1,0]
	v_cvt_f32_f16_e32 v42, v26
	v_cvt_f32_f16_sdwa v43, v26 dst_sel:DWORD dst_unused:UNUSED_PAD src0_sel:WORD_1
	v_pk_mul_f32 v[36:37], v[36:37], v[32:33]
	v_pk_add_f32 v[40:41], v[34:35], -1.0 op_sel_hi:[1,0]
	v_cvt_f32_f16_e32 v44, v30
	v_pk_mul_f32 v[38:39], v[36:37], v[34:35]
	v_pk_fma_f32 v[40:41], v[40:41], v[138:139], 1.0 op_sel_hi:[1,1,0]
	v_cvt_f32_f16_sdwa v45, v30 dst_sel:DWORD dst_unused:UNUSED_PAD src0_sel:WORD_1
	ds_write2st64_b64 v25, v[36:37], v[38:39] offset0:0 offset1:8
	v_pk_mul_f32 v[40:41], v[40:41], v[32:33]
	v_cvt_f32_f16_e32 v26, v29
	v_cvt_f32_f16_sdwa v27, v29 dst_sel:DWORD dst_unused:UNUSED_PAD src0_sel:WORD_1
	ds_write2st64_b64 v25, v[40:41], v[42:43] offset0:16 offset1:24
	s_nop 0
	ds_write2st64_b64 v25, v[44:45], v[26:27] offset0:32 offset1:40
	s_waitcnt lgkmcnt(3)
	v_mov_b32_e32 v26, v98
	v_mov_b32_e32 v27, v99
	v_mov_b32_e32 v30, v100
	v_mov_b32_e32 v31, v101
	v_mov_b32_e32 v29, v97
	v_mov_b32_e32 v28, v96
	v_cvt_f32_f16_e32 v32, v27
	v_cvt_f32_f16_sdwa v33, v27 dst_sel:DWORD dst_unused:UNUSED_PAD src0_sel:WORD_1
	v_cvt_f32_f16_e32 v34, v31
	v_cvt_f32_f16_sdwa v35, v31 dst_sel:DWORD dst_unused:UNUSED_PAD src0_sel:WORD_1
	v_pk_mul_f32 v[36:37], v[136:137], v[28:29] op_sel_hi:[1,0]
	v_cvt_f32_f16_e32 v42, v26
	v_cvt_f32_f16_sdwa v43, v26 dst_sel:DWORD dst_unused:UNUSED_PAD src0_sel:WORD_1
	v_pk_mul_f32 v[36:37], v[36:37], v[32:33]
	v_pk_add_f32 v[40:41], v[34:35], -1.0 op_sel_hi:[1,0]
	v_cvt_f32_f16_e32 v44, v30
	v_pk_mul_f32 v[38:39], v[36:37], v[34:35]
	v_pk_fma_f32 v[40:41], v[40:41], v[138:139], 1.0 op_sel_hi:[1,1,0]
	v_cvt_f32_f16_sdwa v45, v30 dst_sel:DWORD dst_unused:UNUSED_PAD src0_sel:WORD_1
	ds_write2st64_b64 v25, v[36:37], v[38:39] offset0:1 offset1:9
	v_pk_mul_f32 v[40:41], v[40:41], v[32:33]
	v_cvt_f32_f16_e32 v26, v29
	v_cvt_f32_f16_sdwa v27, v29 dst_sel:DWORD dst_unused:UNUSED_PAD src0_sel:WORD_1
	ds_write2st64_b64 v25, v[40:41], v[42:43] offset0:17 offset1:25
	s_nop 0
	ds_write2st64_b64 v25, v[44:45], v[26:27] offset0:33 offset1:41
